# phase 13 epilogue: residual rows fetched in two batches of 16 (addresses and masks first, masked loads into pre-zeroed registers) instead of 16 serial load-wait-store steps
# baseline (speedup 1.0000x reference)
; DI unsigned pk2(float lo, float hi) { f32x2 v = {lo, hi}; bf16x2_t b = __builtin_convertvector(v, bf16x2_t); return __builtin_bit_cast(unsigned, b); }
;     DI void operator()(const f32x4 (&acc)[2][2][4][2], const pg8::Unit& u, int wr, int wc, int fr, int fq) const {
;         const int col0 = u.pn * 256 + wc * 32 + 4 * fq;
; #pragma unroll
;         for (int ai = 0; ai < 2; ++ai)
; #pragma unroll
;             for (int m = 0; m < 4; ++m) { const int r = u.pm * 256 + ai * 128 + wr * 64 + m * 16 + fr; float* rowp = xrow(p, r) + col0; const float* srcp = from_inputs ? x0row(p, r) : xrow(p, r); float ss = 0.f;
; #pragma unroll
;                 for (int bj = 0; bj < 2; ++bj)
; #pragma unroll
;                     for (int n = 0; n < 2; ++n) { const int co = bj * 128 + n * 16; f32x4 x = srcp ? *(const f32x4*)(srcp + col0 + co) : (f32x4){0.f, 0.f, 0.f, 0.f}; x = x + acc[ai][bj][m][n] * alpha; *(f32x4*)(rowp + co) = x;
;                         if (xn) { const f32x4 g = *(const f32x4*)(gnext + col0 + co); ss += x.x * x.x + x.y * x.y + x.z * x.z + x.w * x.w; u32x2 w; w.x = pk2(x.x * g.x, x.y * g.y); w.y = pk2(x.z * g.z, x.w * g.w); *(u32x2*)(xn + (size_t)r * D + col0 + co) = w; } }
;                 if (xn) { ss += __shfl_xor(ss, 16); ss += __shfl_xor(ss, 32); if (fq == 0) atomicAdd(rss + r, ss); } }
;     }
.LBB0_2364:
	s_lshl_b32 s16, s46, 8
	v_add_u32_e32 v128, s16, v150
	v_add_u32_e32 v130, 0xffff7800, v128
	v_cmp_gt_i32_e32 vcc, s42, v128
	v_ashrrev_i32_e32 v129, 31, v128
	v_mov_b32_e32 v131, s31
	v_cndmask_b32_e32 v128, v130, v128, vcc
	v_mov_b32_e32 v130, s35
	v_cndmask_b32_e32 v129, 0, v129, vcc
	v_cndmask_b32_e32 v131, v130, v131, vcc
	v_mov_b32_e32 v130, s34
	v_mov_b32_e32 v132, s30
	v_lshl_or_b32 v146, s45, 8, v159
	v_cndmask_b32_e32 v130, v130, v132, vcc
	v_lshlrev_b64 v[128:129], 12, v[128:129]
	v_ashrrev_i32_e32 v147, 31, v146
	v_lshl_add_u64 v[128:129], v[130:131], 0, v[128:129]
	v_lshl_add_u64 v[148:149], v[146:147], 2, v[128:129]
	v_cmp_ne_u64_e32 vcc, 0, v[130:131]
	v_mov_b32_e32 v164, 0
	v_mov_b32_e32 v165, 0
	v_mov_b32_e32 v166, 0
	v_mov_b32_e32 v167, 0
	v_mov_b32_e32 v168, 0
	v_mov_b32_e32 v169, 0
	v_mov_b32_e32 v170, 0
	v_mov_b32_e32 v171, 0
	v_mov_b32_e32 v172, 0
	v_mov_b32_e32 v173, 0
	v_mov_b32_e32 v174, 0
	v_mov_b32_e32 v175, 0
	v_mov_b32_e32 v176, 0
	v_mov_b32_e32 v177, 0
	v_mov_b32_e32 v178, 0
	v_mov_b32_e32 v179, 0
	s_and_saveexec_b64 s[48:49], vcc
	global_load_dwordx4 v[164:167], v[148:149], off
	global_load_dwordx4 v[168:171], v[148:149], off offset:64
	global_load_dwordx4 v[172:175], v[148:149], off offset:512
	global_load_dwordx4 v[176:179], v[148:149], off offset:576
	s_or_b64 exec, exec, s[48:49]
	v_mov_b32_e32 v132, s30
	v_add_u32_e32 v128, s16, v152
	v_add_u32_e32 v130, 0xffff7800, v128
	v_cmp_gt_i32_e32 vcc, s42, v128
	v_ashrrev_i32_e32 v129, 31, v128
	v_mov_b32_e32 v131, s31
	v_cndmask_b32_e32 v128, v130, v128, vcc
	v_mov_b32_e32 v130, s35
	v_cndmask_b32_e32 v129, 0, v129, vcc
	v_cndmask_b32_e32 v131, v130, v131, vcc
	v_mov_b32_e32 v130, s34
	v_cndmask_b32_e32 v130, v130, v132, vcc
	v_lshlrev_b64 v[128:129], 12, v[128:129]
	v_lshl_add_u64 v[128:129], v[130:131], 0, v[128:129]
	v_lshl_add_u64 v[214:215], v[146:147], 2, v[128:129]
	v_cmp_ne_u64_e32 vcc, 0, v[130:131]
	v_mov_b32_e32 v180, 0
	v_mov_b32_e32 v181, 0
	v_mov_b32_e32 v182, 0
	v_mov_b32_e32 v183, 0
	v_mov_b32_e32 v184, 0
	v_mov_b32_e32 v185, 0
	v_mov_b32_e32 v186, 0
	v_mov_b32_e32 v187, 0
	v_mov_b32_e32 v188, 0
	v_mov_b32_e32 v189, 0
	v_mov_b32_e32 v190, 0
	v_mov_b32_e32 v191, 0
	v_mov_b32_e32 v192, 0
	v_mov_b32_e32 v193, 0
	v_mov_b32_e32 v194, 0
	v_mov_b32_e32 v195, 0
	s_and_saveexec_b64 s[48:49], vcc
	global_load_dwordx4 v[180:183], v[214:215], off
	global_load_dwordx4 v[184:187], v[214:215], off offset:64
	global_load_dwordx4 v[188:191], v[214:215], off offset:512
	global_load_dwordx4 v[192:195], v[214:215], off offset:576
	s_or_b64 exec, exec, s[48:49]
	v_mov_b32_e32 v132, s30
	v_add_u32_e32 v128, s16, v153
	v_add_u32_e32 v130, 0xffff7800, v128
	v_cmp_gt_i32_e32 vcc, s42, v128
	v_ashrrev_i32_e32 v129, 31, v128
	v_mov_b32_e32 v131, s31
	v_cndmask_b32_e32 v128, v130, v128, vcc
	v_mov_b32_e32 v130, s35
	v_cndmask_b32_e32 v129, 0, v129, vcc
	v_cndmask_b32_e32 v131, v130, v131, vcc
	v_mov_b32_e32 v130, s34
	v_cndmask_b32_e32 v130, v130, v132, vcc
	v_lshlrev_b64 v[128:129], 12, v[128:129]
	v_lshl_add_u64 v[128:129], v[130:131], 0, v[128:129]
	v_lshl_add_u64 v[232:233], v[146:147], 2, v[128:129]
	v_cmp_ne_u64_e32 vcc, 0, v[130:131]
	v_mov_b32_e32 v196, 0
	v_mov_b32_e32 v197, 0
	v_mov_b32_e32 v198, 0
	v_mov_b32_e32 v199, 0
	v_mov_b32_e32 v200, 0
	v_mov_b32_e32 v201, 0
	v_mov_b32_e32 v202, 0
	v_mov_b32_e32 v203, 0
	v_mov_b32_e32 v204, 0
	v_mov_b32_e32 v205, 0
	v_mov_b32_e32 v206, 0
	v_mov_b32_e32 v207, 0
	v_mov_b32_e32 v208, 0
	v_mov_b32_e32 v209, 0
	v_mov_b32_e32 v210, 0
	v_mov_b32_e32 v211, 0
	s_and_saveexec_b64 s[48:49], vcc
	global_load_dwordx4 v[196:199], v[232:233], off
	global_load_dwordx4 v[200:203], v[232:233], off offset:64
	global_load_dwordx4 v[204:207], v[232:233], off offset:512
	global_load_dwordx4 v[208:211], v[232:233], off offset:576
	s_or_b64 exec, exec, s[48:49]
	v_mov_b32_e32 v132, s30
	v_add_u32_e32 v128, s16, v154
	v_add_u32_e32 v130, 0xffff7800, v128
	v_cmp_gt_i32_e32 vcc, s42, v128
	v_ashrrev_i32_e32 v129, 31, v128
	v_mov_b32_e32 v131, s31
	v_cndmask_b32_e32 v128, v130, v128, vcc
	v_mov_b32_e32 v130, s35
	v_cndmask_b32_e32 v129, 0, v129, vcc
	v_cndmask_b32_e32 v131, v130, v131, vcc
	v_mov_b32_e32 v130, s34
	v_cndmask_b32_e32 v130, v130, v132, vcc
	v_lshlrev_b64 v[128:129], 12, v[128:129]
	v_lshl_add_u64 v[128:129], v[130:131], 0, v[128:129]
	v_lshl_add_u64 v[234:235], v[146:147], 2, v[128:129]
	v_cmp_ne_u64_e32 vcc, 0, v[130:131]
	v_mov_b32_e32 v216, 0
	v_mov_b32_e32 v217, 0
	v_mov_b32_e32 v218, 0
	v_mov_b32_e32 v219, 0
	v_mov_b32_e32 v220, 0
	v_mov_b32_e32 v221, 0
	v_mov_b32_e32 v222, 0
	v_mov_b32_e32 v223, 0
	v_mov_b32_e32 v224, 0
	v_mov_b32_e32 v225, 0
	v_mov_b32_e32 v226, 0
	v_mov_b32_e32 v227, 0
	v_mov_b32_e32 v228, 0
	v_mov_b32_e32 v229, 0
	v_mov_b32_e32 v230, 0
	v_mov_b32_e32 v231, 0
	s_and_saveexec_b64 s[48:49], vcc
	global_load_dwordx4 v[216:219], v[234:235], off
	global_load_dwordx4 v[220:223], v[234:235], off offset:64
	global_load_dwordx4 v[224:227], v[234:235], off offset:512
	global_load_dwordx4 v[228:231], v[234:235], off offset:576
	s_or_b64 exec, exec, s[48:49]
	s_waitcnt vmcnt(12)
	v_pk_fma_f32 v[166:167], v[126:127], 0.5, v[166:167] op_sel_hi:[1,0,1]
	v_pk_fma_f32 v[164:165], v[124:125], 0.5, v[164:165] op_sel_hi:[1,0,1]
	v_pk_fma_f32 v[170:171], v[122:123], 0.5, v[170:171] op_sel_hi:[1,0,1]
	v_pk_fma_f32 v[168:169], v[120:121], 0.5, v[168:169] op_sel_hi:[1,0,1]
	v_pk_fma_f32 v[174:175], v[118:119], 0.5, v[174:175] op_sel_hi:[1,0,1]
	v_pk_fma_f32 v[172:173], v[116:117], 0.5, v[172:173] op_sel_hi:[1,0,1]
	v_pk_fma_f32 v[178:179], v[114:115], 0.5, v[178:179] op_sel_hi:[1,0,1]
	v_pk_fma_f32 v[176:177], v[112:113], 0.5, v[176:177] op_sel_hi:[1,0,1]
	global_store_dwordx4 v[148:149], v[164:167], off
	global_store_dwordx4 v[148:149], v[168:171], off offset:64
	global_store_dwordx4 v[148:149], v[172:175], off offset:512
	global_store_dwordx4 v[148:149], v[176:179], off offset:576
	s_waitcnt vmcnt(12)
; DI unsigned pk2(float lo, float hi) { f32x2 v = {lo, hi}; bf16x2_t b = __builtin_convertvector(v, bf16x2_t); return __builtin_bit_cast(unsigned, b); }
;     DI void operator()(const f32x4 (&acc)[2][2][4][2], const pg8::Unit& u, int wr, int wc, int fr, int fq) const {
;         const int col0 = u.pn * 256 + wc * 32 + 4 * fq;
; #pragma unroll
;         for (int ai = 0; ai < 2; ++ai)
; #pragma unroll
;             for (int m = 0; m < 4; ++m) { const int r = u.pm * 256 + ai * 128 + wr * 64 + m * 16 + fr; float* rowp = xrow(p, r) + col0; const float* srcp = from_inputs ? x0row(p, r) : xrow(p, r); float ss = 0.f;
; #pragma unroll
;                 for (int bj = 0; bj < 2; ++bj)
; #pragma unroll
;                     for (int n = 0; n < 2; ++n) { const int co = bj * 128 + n * 16; f32x4 x = srcp ? *(const f32x4*)(srcp + col0 + co) : (f32x4){0.f, 0.f, 0.f, 0.f}; x = x + acc[ai][bj][m][n] * alpha; *(f32x4*)(rowp + co) = x;
;                         if (xn) { const f32x4 g = *(const f32x4*)(gnext + col0 + co); ss += x.x * x.x + x.y * x.y + x.z * x.z + x.w * x.w; u32x2 w; w.x = pk2(x.x * g.x, x.y * g.y); w.y = pk2(x.z * g.z, x.w * g.w); *(u32x2*)(xn + (size_t)r * D + col0 + co) = w; } }
;                 if (xn) { ss += __shfl_xor(ss, 16); ss += __shfl_xor(ss, 32); if (fq == 0) atomicAdd(rss + r, ss); } }
;     }
	v_pk_fma_f32 v[182:183], v[110:111], 0.5, v[182:183] op_sel_hi:[1,0,1]
	v_pk_fma_f32 v[180:181], v[108:109], 0.5, v[180:181] op_sel_hi:[1,0,1]
	v_pk_fma_f32 v[186:187], v[106:107], 0.5, v[186:187] op_sel_hi:[1,0,1]
	v_pk_fma_f32 v[184:185], v[104:105], 0.5, v[184:185] op_sel_hi:[1,0,1]
	v_pk_fma_f32 v[190:191], v[102:103], 0.5, v[190:191] op_sel_hi:[1,0,1]
	v_pk_fma_f32 v[188:189], v[100:101], 0.5, v[188:189] op_sel_hi:[1,0,1]
	v_pk_fma_f32 v[194:195], v[98:99], 0.5, v[194:195] op_sel_hi:[1,0,1]
	v_pk_fma_f32 v[192:193], v[96:97], 0.5, v[192:193] op_sel_hi:[1,0,1]
	global_store_dwordx4 v[214:215], v[180:183], off
	global_store_dwordx4 v[214:215], v[184:187], off offset:64
	global_store_dwordx4 v[214:215], v[188:191], off offset:512
	global_store_dwordx4 v[214:215], v[192:195], off offset:576
	s_waitcnt vmcnt(12)
	v_pk_fma_f32 v[198:199], v[94:95], 0.5, v[198:199] op_sel_hi:[1,0,1]
	v_pk_fma_f32 v[196:197], v[92:93], 0.5, v[196:197] op_sel_hi:[1,0,1]
	v_pk_fma_f32 v[202:203], v[90:91], 0.5, v[202:203] op_sel_hi:[1,0,1]
	v_pk_fma_f32 v[200:201], v[88:89], 0.5, v[200:201] op_sel_hi:[1,0,1]
	v_pk_fma_f32 v[206:207], v[86:87], 0.5, v[206:207] op_sel_hi:[1,0,1]
	v_pk_fma_f32 v[204:205], v[84:85], 0.5, v[204:205] op_sel_hi:[1,0,1]
	v_pk_fma_f32 v[210:211], v[82:83], 0.5, v[210:211] op_sel_hi:[1,0,1]
	v_pk_fma_f32 v[208:209], v[80:81], 0.5, v[208:209] op_sel_hi:[1,0,1]
	global_store_dwordx4 v[232:233], v[196:199], off
	global_store_dwordx4 v[232:233], v[200:203], off offset:64
	global_store_dwordx4 v[232:233], v[204:207], off offset:512
	global_store_dwordx4 v[232:233], v[208:211], off offset:576
	s_waitcnt vmcnt(12)
	v_pk_fma_f32 v[218:219], v[78:79], 0.5, v[218:219] op_sel_hi:[1,0,1]
	v_pk_fma_f32 v[216:217], v[76:77], 0.5, v[216:217] op_sel_hi:[1,0,1]
	v_pk_fma_f32 v[222:223], v[74:75], 0.5, v[222:223] op_sel_hi:[1,0,1]
	v_pk_fma_f32 v[220:221], v[72:73], 0.5, v[220:221] op_sel_hi:[1,0,1]
	v_pk_fma_f32 v[226:227], v[70:71], 0.5, v[226:227] op_sel_hi:[1,0,1]
	v_pk_fma_f32 v[224:225], v[68:69], 0.5, v[224:225] op_sel_hi:[1,0,1]
	v_pk_fma_f32 v[230:231], v[66:67], 0.5, v[230:231] op_sel_hi:[1,0,1]
	v_pk_fma_f32 v[228:229], v[64:65], 0.5, v[228:229] op_sel_hi:[1,0,1]
	global_store_dwordx4 v[234:235], v[216:219], off
	global_store_dwordx4 v[234:235], v[220:223], off offset:64
	global_store_dwordx4 v[234:235], v[224:227], off offset:512
	global_store_dwordx4 v[234:235], v[228:231], off offset:576
	v_mov_b32_e32 v132, s30
	v_add_u32_e32 v128, s16, v155
	v_add_u32_e32 v130, 0xffff7800, v128
	v_cmp_gt_i32_e32 vcc, s42, v128
	v_ashrrev_i32_e32 v129, 31, v128
	v_mov_b32_e32 v131, s31
	v_cndmask_b32_e32 v128, v130, v128, vcc
	v_mov_b32_e32 v130, s35
	v_cndmask_b32_e32 v129, 0, v129, vcc
	v_cndmask_b32_e32 v131, v130, v131, vcc
	v_mov_b32_e32 v130, s34
	v_cndmask_b32_e32 v130, v130, v132, vcc
	v_lshlrev_b64 v[128:129], 12, v[128:129]
	v_lshl_add_u64 v[128:129], v[130:131], 0, v[128:129]
	v_lshl_add_u64 v[148:149], v[146:147], 2, v[128:129]
	v_cmp_ne_u64_e32 vcc, 0, v[130:131]
	v_mov_b32_e32 v164, 0
	v_mov_b32_e32 v165, 0
	v_mov_b32_e32 v166, 0
	v_mov_b32_e32 v167, 0
	v_mov_b32_e32 v168, 0
	v_mov_b32_e32 v169, 0
	v_mov_b32_e32 v170, 0
	v_mov_b32_e32 v171, 0
	v_mov_b32_e32 v172, 0
	v_mov_b32_e32 v173, 0
	v_mov_b32_e32 v174, 0
	v_mov_b32_e32 v175, 0
	v_mov_b32_e32 v176, 0
	v_mov_b32_e32 v177, 0
	v_mov_b32_e32 v178, 0
	v_mov_b32_e32 v179, 0
	s_and_saveexec_b64 s[48:49], vcc
	global_load_dwordx4 v[164:167], v[148:149], off
	global_load_dwordx4 v[168:171], v[148:149], off offset:64
	global_load_dwordx4 v[172:175], v[148:149], off offset:512
	global_load_dwordx4 v[176:179], v[148:149], off offset:576
	s_or_b64 exec, exec, s[48:49]
	v_mov_b32_e32 v132, s30
	v_add_u32_e32 v128, s16, v156
	v_add_u32_e32 v130, 0xffff7800, v128
	v_cmp_gt_i32_e32 vcc, s42, v128
	v_ashrrev_i32_e32 v129, 31, v128
	v_mov_b32_e32 v131, s31
	v_cndmask_b32_e32 v128, v130, v128, vcc
	v_mov_b32_e32 v130, s35
	v_cndmask_b32_e32 v129, 0, v129, vcc
	v_cndmask_b32_e32 v131, v130, v131, vcc
	v_mov_b32_e32 v130, s34
	v_cndmask_b32_e32 v130, v130, v132, vcc
	v_lshlrev_b64 v[128:129], 12, v[128:129]
	v_lshl_add_u64 v[128:129], v[130:131], 0, v[128:129]
	v_lshl_add_u64 v[214:215], v[146:147], 2, v[128:129]
	v_cmp_ne_u64_e32 vcc, 0, v[130:131]
	v_mov_b32_e32 v180, 0
	v_mov_b32_e32 v181, 0
	v_mov_b32_e32 v182, 0
	v_mov_b32_e32 v183, 0
	v_mov_b32_e32 v184, 0
	v_mov_b32_e32 v185, 0
	v_mov_b32_e32 v186, 0
	v_mov_b32_e32 v187, 0
	v_mov_b32_e32 v188, 0
	v_mov_b32_e32 v189, 0
	v_mov_b32_e32 v190, 0
	v_mov_b32_e32 v191, 0
	v_mov_b32_e32 v192, 0
	v_mov_b32_e32 v193, 0
	v_mov_b32_e32 v194, 0
	v_mov_b32_e32 v195, 0
	s_and_saveexec_b64 s[48:49], vcc
	global_load_dwordx4 v[180:183], v[214:215], off
	global_load_dwordx4 v[184:187], v[214:215], off offset:64
	global_load_dwordx4 v[188:191], v[214:215], off offset:512
	global_load_dwordx4 v[192:195], v[214:215], off offset:576
	s_or_b64 exec, exec, s[48:49]
	v_mov_b32_e32 v132, s30
	v_add_u32_e32 v128, s16, v157
	v_add_u32_e32 v130, 0xffff7800, v128
	v_cmp_gt_i32_e32 vcc, s42, v128
	v_ashrrev_i32_e32 v129, 31, v128
	v_mov_b32_e32 v131, s31
	v_cndmask_b32_e32 v128, v130, v128, vcc
	v_mov_b32_e32 v130, s35
	v_cndmask_b32_e32 v129, 0, v129, vcc
	v_cndmask_b32_e32 v131, v130, v131, vcc
	v_mov_b32_e32 v130, s34
	v_cndmask_b32_e32 v130, v130, v132, vcc
	v_lshlrev_b64 v[128:129], 12, v[128:129]
	v_lshl_add_u64 v[128:129], v[130:131], 0, v[128:129]
; DI unsigned pk2(float lo, float hi) { f32x2 v = {lo, hi}; bf16x2_t b = __builtin_convertvector(v, bf16x2_t); return __builtin_bit_cast(unsigned, b); }
;     DI void operator()(const f32x4 (&acc)[2][2][4][2], const pg8::Unit& u, int wr, int wc, int fr, int fq) const {
;         const int col0 = u.pn * 256 + wc * 32 + 4 * fq;
; #pragma unroll
;         for (int ai = 0; ai < 2; ++ai)
; #pragma unroll
;             for (int m = 0; m < 4; ++m) { const int r = u.pm * 256 + ai * 128 + wr * 64 + m * 16 + fr; float* rowp = xrow(p, r) + col0; const float* srcp = from_inputs ? x0row(p, r) : xrow(p, r); float ss = 0.f;
; #pragma unroll
;                 for (int bj = 0; bj < 2; ++bj)
; #pragma unroll
;                     for (int n = 0; n < 2; ++n) { const int co = bj * 128 + n * 16; f32x4 x = srcp ? *(const f32x4*)(srcp + col0 + co) : (f32x4){0.f, 0.f, 0.f, 0.f}; x = x + acc[ai][bj][m][n] * alpha; *(f32x4*)(rowp + co) = x;
;                         if (xn) { const f32x4 g = *(const f32x4*)(gnext + col0 + co); ss += x.x * x.x + x.y * x.y + x.z * x.z + x.w * x.w; u32x2 w; w.x = pk2(x.x * g.x, x.y * g.y); w.y = pk2(x.z * g.z, x.w * g.w); *(u32x2*)(xn + (size_t)r * D + col0 + co) = w; } }
;                 if (xn) { ss += __shfl_xor(ss, 16); ss += __shfl_xor(ss, 32); if (fq == 0) atomicAdd(rss + r, ss); } }
;     }
	v_lshl_add_u64 v[232:233], v[146:147], 2, v[128:129]
	v_cmp_ne_u64_e32 vcc, 0, v[130:131]
	v_mov_b32_e32 v196, 0
	v_mov_b32_e32 v197, 0
	v_mov_b32_e32 v198, 0
	v_mov_b32_e32 v199, 0
	v_mov_b32_e32 v200, 0
	v_mov_b32_e32 v201, 0
	v_mov_b32_e32 v202, 0
	v_mov_b32_e32 v203, 0
	v_mov_b32_e32 v204, 0
	v_mov_b32_e32 v205, 0
	v_mov_b32_e32 v206, 0
	v_mov_b32_e32 v207, 0
	v_mov_b32_e32 v208, 0
	v_mov_b32_e32 v209, 0
	v_mov_b32_e32 v210, 0
	v_mov_b32_e32 v211, 0
	s_and_saveexec_b64 s[48:49], vcc
	global_load_dwordx4 v[196:199], v[232:233], off
	global_load_dwordx4 v[200:203], v[232:233], off offset:64
	global_load_dwordx4 v[204:207], v[232:233], off offset:512
	global_load_dwordx4 v[208:211], v[232:233], off offset:576
	s_or_b64 exec, exec, s[48:49]
	v_mov_b32_e32 v132, s30
	v_add_u32_e32 v128, s16, v158
	v_add_u32_e32 v130, 0xffff7800, v128
	v_cmp_gt_i32_e32 vcc, s42, v128
	v_ashrrev_i32_e32 v129, 31, v128
	v_mov_b32_e32 v131, s31
	v_cndmask_b32_e32 v128, v130, v128, vcc
	v_mov_b32_e32 v130, s35
	v_cndmask_b32_e32 v129, 0, v129, vcc
	v_cndmask_b32_e32 v131, v130, v131, vcc
	v_mov_b32_e32 v130, s34
	v_cndmask_b32_e32 v130, v130, v132, vcc
	v_lshlrev_b64 v[128:129], 12, v[128:129]
	v_lshl_add_u64 v[128:129], v[130:131], 0, v[128:129]
	v_lshl_add_u64 v[234:235], v[146:147], 2, v[128:129]
	v_cmp_ne_u64_e32 vcc, 0, v[130:131]
	v_mov_b32_e32 v216, 0
	v_mov_b32_e32 v217, 0
	v_mov_b32_e32 v218, 0
	v_mov_b32_e32 v219, 0
	v_mov_b32_e32 v220, 0
	v_mov_b32_e32 v221, 0
	v_mov_b32_e32 v222, 0
	v_mov_b32_e32 v223, 0
	v_mov_b32_e32 v224, 0
	v_mov_b32_e32 v225, 0
	v_mov_b32_e32 v226, 0
	v_mov_b32_e32 v227, 0
	v_mov_b32_e32 v228, 0
	v_mov_b32_e32 v229, 0
	v_mov_b32_e32 v230, 0
	v_mov_b32_e32 v231, 0
	s_and_saveexec_b64 s[48:49], vcc
	global_load_dwordx4 v[216:219], v[234:235], off
	global_load_dwordx4 v[220:223], v[234:235], off offset:64
	global_load_dwordx4 v[224:227], v[234:235], off offset:512
	global_load_dwordx4 v[228:231], v[234:235], off offset:576
	s_or_b64 exec, exec, s[48:49]
	s_waitcnt vmcnt(12)
	v_pk_fma_f32 v[166:167], v[62:63], 0.5, v[166:167] op_sel_hi:[1,0,1]
	v_pk_fma_f32 v[164:165], v[60:61], 0.5, v[164:165] op_sel_hi:[1,0,1]
	v_pk_fma_f32 v[170:171], v[58:59], 0.5, v[170:171] op_sel_hi:[1,0,1]
	v_pk_fma_f32 v[168:169], v[56:57], 0.5, v[168:169] op_sel_hi:[1,0,1]
	v_pk_fma_f32 v[174:175], v[54:55], 0.5, v[174:175] op_sel_hi:[1,0,1]
	v_pk_fma_f32 v[172:173], v[52:53], 0.5, v[172:173] op_sel_hi:[1,0,1]
	v_pk_fma_f32 v[178:179], v[50:51], 0.5, v[178:179] op_sel_hi:[1,0,1]
	v_pk_fma_f32 v[176:177], v[48:49], 0.5, v[176:177] op_sel_hi:[1,0,1]
	global_store_dwordx4 v[148:149], v[164:167], off
	global_store_dwordx4 v[148:149], v[168:171], off offset:64
	global_store_dwordx4 v[148:149], v[172:175], off offset:512
	global_store_dwordx4 v[148:149], v[176:179], off offset:576
	s_waitcnt vmcnt(12)
	v_pk_fma_f32 v[182:183], v[46:47], 0.5, v[182:183] op_sel_hi:[1,0,1]
	v_pk_fma_f32 v[180:181], v[44:45], 0.5, v[180:181] op_sel_hi:[1,0,1]
	v_pk_fma_f32 v[186:187], v[42:43], 0.5, v[186:187] op_sel_hi:[1,0,1]
	v_pk_fma_f32 v[184:185], v[40:41], 0.5, v[184:185] op_sel_hi:[1,0,1]
	v_pk_fma_f32 v[190:191], v[38:39], 0.5, v[190:191] op_sel_hi:[1,0,1]
	v_pk_fma_f32 v[188:189], v[36:37], 0.5, v[188:189] op_sel_hi:[1,0,1]
	v_pk_fma_f32 v[194:195], v[34:35], 0.5, v[194:195] op_sel_hi:[1,0,1]
	v_pk_fma_f32 v[192:193], v[32:33], 0.5, v[192:193] op_sel_hi:[1,0,1]
	global_store_dwordx4 v[214:215], v[180:183], off
	global_store_dwordx4 v[214:215], v[184:187], off offset:64
	global_store_dwordx4 v[214:215], v[188:191], off offset:512
	global_store_dwordx4 v[214:215], v[192:195], off offset:576
	s_waitcnt vmcnt(12)
	v_pk_fma_f32 v[198:199], v[30:31], 0.5, v[198:199] op_sel_hi:[1,0,1]
	v_pk_fma_f32 v[196:197], v[28:29], 0.5, v[196:197] op_sel_hi:[1,0,1]
	v_pk_fma_f32 v[202:203], v[26:27], 0.5, v[202:203] op_sel_hi:[1,0,1]
	v_pk_fma_f32 v[200:201], v[24:25], 0.5, v[200:201] op_sel_hi:[1,0,1]
	v_pk_fma_f32 v[206:207], v[22:23], 0.5, v[206:207] op_sel_hi:[1,0,1]
	v_pk_fma_f32 v[204:205], v[20:21], 0.5, v[204:205] op_sel_hi:[1,0,1]
	v_pk_fma_f32 v[210:211], v[18:19], 0.5, v[210:211] op_sel_hi:[1,0,1]
	v_pk_fma_f32 v[208:209], v[16:17], 0.5, v[208:209] op_sel_hi:[1,0,1]
	global_store_dwordx4 v[232:233], v[196:199], off
	global_store_dwordx4 v[232:233], v[200:203], off offset:64
	global_store_dwordx4 v[232:233], v[204:207], off offset:512
	global_store_dwordx4 v[232:233], v[208:211], off offset:576
	s_waitcnt vmcnt(12)
	v_pk_fma_f32 v[218:219], v[14:15], 0.5, v[218:219] op_sel_hi:[1,0,1]
	v_pk_fma_f32 v[216:217], v[12:13], 0.5, v[216:217] op_sel_hi:[1,0,1]
	v_pk_fma_f32 v[222:223], v[10:11], 0.5, v[222:223] op_sel_hi:[1,0,1]
	v_pk_fma_f32 v[220:221], v[8:9], 0.5, v[220:221] op_sel_hi:[1,0,1]
	v_pk_fma_f32 v[226:227], v[6:7], 0.5, v[226:227] op_sel_hi:[1,0,1]
	v_pk_fma_f32 v[224:225], v[4:5], 0.5, v[224:225] op_sel_hi:[1,0,1]
	v_pk_fma_f32 v[230:231], v[2:3], 0.5, v[230:231] op_sel_hi:[1,0,1]
	v_pk_fma_f32 v[228:229], v[0:1], 0.5, v[228:229] op_sel_hi:[1,0,1]
	global_store_dwordx4 v[234:235], v[216:219], off
	global_store_dwordx4 v[234:235], v[220:223], off offset:64
	global_store_dwordx4 v[234:235], v[224:227], off offset:512
	global_store_dwordx4 v[234:235], v[228:231], off offset:576
	s_and_b64 vcc, exec, s[0:1]
	s_mov_b64 s[0:1], -1
	s_cbranch_vccnz .LBB0_2347
	s_andn2_b64 vcc, exec, s[4:5]
	s_cbranch_vccnz .LBB0_2346
	s_barrier
	s_branch .LBB0_2346
